# residual GEMM whole units: residual tile folded into accumulators during the K loop (2 quad loads per iteration inside the counted vmcnt scheme), epilogue stores only
# speedup vs baseline: 1.0187x; 1.0187x over previous
.Lrk_344:
	s_add_i32 vcc_lo, s50, 2
	s_add_u32 s68, s48, 0x80
	s_addc_u32 s51, s49, 0
	s_add_i32 s70, 0, 0x10000
	s_cmp_eq_u32 s15, s50
	s_cselect_b32 s51, s1, s51
	s_cselect_b32 s50, s0, s68
	v_add_u32_e32 v0, s70, v223
	s_cselect_b32 s69, s53, s57
	s_cselect_b32 s68, s52, s56
	s_add_i32 s71, 0, 0x14000
	ds_read_b128 v[130:133], v0
	ds_read_b128 v[134:137], v0 offset:1024
	ds_read_b128 v[138:141], v0 offset:2048
	ds_read_b128 v[142:145], v0 offset:3072
	v_add_u32_e32 v0, s71, v223
	ds_read_b128 v[146:149], v0
	ds_read_b128 v[150:153], v0 offset:1024
	ds_read_b128 v[154:157], v0 offset:2048
	ds_read_b128 v[158:161], v0 offset:3072
	s_add_i32 s98, vcc_lo, -2
	s_lshr_b32 s99, s98, 3
	s_lshl_b32 s99, s99, 17
	s_and_b32 vcc_hi, s98, 2
	s_lshl_b32 vcc_hi, vcc_hi, 5
	s_or_b32 s99, s99, vcc_hi
	s_and_b32 vcc_hi, s98, 4
	s_lshl_b32 vcc_hi, vcc_hi, 7
	s_or_b32 s98, s99, vcc_hi
	s_add_u32 s98, s100, s98
	s_addc_u32 s99, s101, 0
	s_nop 0
	global_load_dwordx4 v[240:243], v238, s[98:99]
	v_lshl_add_u64 v[212:213], s[48:49], 0, v[192:193]
	s_add_i32 m0, s67, 0xc000
	ds_read_b128 v[162:165], v226
	ds_read_b128 v[166:169], v226 offset:1024
	ds_read_b128 v[170:173], v226 offset:2048
	ds_read_b128 v[174:177], v226 offset:3072
	ds_read_b128 v[196:199], v226 offset:4096
	ds_read_b128 v[200:203], v226 offset:5120
	ds_read_b128 v[204:207], v226 offset:6144
	ds_read_b128 v[208:211], v226 offset:7168
	global_load_lds_dwordx4 v[212:213], off
	v_lshl_add_u64 v[212:213], s[48:49], 0, v[194:195]
	s_add_i32 m0, s67, 0xe000
	s_nop 0
	global_load_lds_dwordx4 v[212:213], off
	s_waitcnt vmcnt(9)
	s_waitcnt lgkmcnt(0)
	s_barrier
	s_setprio 1
	s_waitcnt lgkmcnt(0)
	v_mfma_f32_16x16x32_bf16 v[126:129], v[130:133], v[162:165], v[126:129]
	v_mfma_f32_16x16x32_bf16 v[122:125], v[138:141], v[162:165], v[122:125]
	v_mfma_f32_16x16x32_bf16 v[118:121], v[130:133], v[170:173], v[118:121]
	v_mfma_f32_16x16x32_bf16 v[114:117], v[138:141], v[170:173], v[114:117]
	v_mfma_f32_16x16x32_bf16 v[102:105], v[130:133], v[196:199], v[102:105]
	v_mfma_f32_16x16x32_bf16 v[98:101], v[138:141], v[196:199], v[98:101]
	v_mfma_f32_16x16x32_bf16 v[86:89], v[130:133], v[204:207], v[86:89]
	v_mfma_f32_16x16x32_bf16 v[82:85], v[138:141], v[204:207], v[82:85]
	v_mfma_f32_16x16x32_bf16 v[126:129], v[134:137], v[166:169], v[126:129]
	v_mfma_f32_16x16x32_bf16 v[122:125], v[142:145], v[166:169], v[122:125]
	v_mfma_f32_16x16x32_bf16 v[118:121], v[134:137], v[174:177], v[118:121]
	v_mfma_f32_16x16x32_bf16 v[114:117], v[142:145], v[174:177], v[114:117]
	v_mfma_f32_16x16x32_bf16 v[102:105], v[134:137], v[200:203], v[102:105]
	v_mfma_f32_16x16x32_bf16 v[98:101], v[142:145], v[200:203], v[98:101]
	v_mfma_f32_16x16x32_bf16 v[86:89], v[134:137], v[208:211], v[86:89]
	v_mfma_f32_16x16x32_bf16 v[82:85], v[142:145], v[208:211], v[82:85]
	s_setprio 0
	s_setprio 1
	v_mfma_f32_16x16x32_bf16 v[110:113], v[146:149], v[162:165], v[110:113]
	v_mfma_f32_16x16x32_bf16 v[106:109], v[154:157], v[162:165], v[106:109]
	v_mfma_f32_16x16x32_bf16 v[94:97], v[146:149], v[170:173], v[94:97]
	v_mfma_f32_16x16x32_bf16 v[90:93], v[154:157], v[170:173], v[90:93]
	v_mfma_f32_16x16x32_bf16 v[78:81], v[146:149], v[196:199], v[78:81]
	v_mfma_f32_16x16x32_bf16 v[74:77], v[154:157], v[196:199], v[74:77]
	v_mfma_f32_16x16x32_bf16 v[70:73], v[146:149], v[204:207], v[70:73]
	v_mfma_f32_16x16x32_bf16 v[66:69], v[154:157], v[204:207], v[66:69]
	v_mfma_f32_16x16x32_bf16 v[110:113], v[150:153], v[166:169], v[110:113]
	v_mfma_f32_16x16x32_bf16 v[106:109], v[158:161], v[166:169], v[106:109]
	v_mfma_f32_16x16x32_bf16 v[94:97], v[150:153], v[174:177], v[94:97]
	v_mfma_f32_16x16x32_bf16 v[90:93], v[158:161], v[174:177], v[90:93]
	v_mfma_f32_16x16x32_bf16 v[78:81], v[150:153], v[200:203], v[78:81]
	v_mfma_f32_16x16x32_bf16 v[74:77], v[158:161], v[200:203], v[74:77]
	v_mfma_f32_16x16x32_bf16 v[70:73], v[150:153], v[208:211], v[70:73]
	v_mfma_f32_16x16x32_bf16 v[66:69], v[158:161], v[208:211], v[66:69]
	s_setprio 0
	s_barrier
	s_add_i32 s70, s70, s63
	v_lshl_add_u64 v[212:213], s[68:69], 0, v[186:187]
	s_mov_b32 m0, s70
	ds_read_b128 v[162:165], v226 offset:16384
	ds_read_b128 v[166:169], v226 offset:17408
	ds_read_b128 v[170:173], v226 offset:18432
	ds_read_b128 v[174:177], v226 offset:19456
	ds_read_b128 v[196:199], v226 offset:20480
	ds_read_b128 v[200:203], v226 offset:21504
	ds_read_b128 v[204:207], v226 offset:22528
	ds_read_b128 v[208:211], v226 offset:23552
	global_load_lds_dwordx4 v[212:213], off
	s_add_i32 m0, s70, 0x2000
	v_lshl_add_u64 v[214:215], s[68:69], 0, v[182:183]
	s_add_u32 s68, s68, s90
	s_addc_u32 s69, s69, 0
	s_add_i32 s70, s71, s63
	global_load_lds_dwordx4 v[214:215], off
	v_lshl_add_u64 v[216:217], s[68:69], 0, v[186:187]
	s_mov_b32 m0, s70
	v_lshl_add_u64 v[218:219], s[68:69], 0, v[182:183]
	global_load_lds_dwordx4 v[216:217], off
	s_add_i32 m0, s70, 0x2000
	v_lshl_add_u64 v[232:233], s[50:51], 0, v[184:185]
	global_load_lds_dwordx4 v[218:219], off
	s_mov_b32 m0, s67
	v_lshl_add_u64 v[234:235], s[50:51], 0, v[180:181]
	global_load_lds_dwordx4 v[232:233], off
	s_mov_b32 m0, s33
	s_nop 0
	global_load_lds_dwordx4 v[234:235], off
	s_waitcnt vmcnt(8)
	s_add_i32 s98, vcc_lo, -2
	s_cmp_lt_u32 s98, 16
	s_cbranch_scc0 .Lrk_dU_8_16
	s_cmp_lt_u32 s98, 8
	s_cbranch_scc0 .Lrk_dU_4_8
	s_cmp_lt_u32 s98, 4
	s_cbranch_scc0 .Lrk_dU_2_4
	s_cmp_lt_u32 s98, 2
	s_cbranch_scc0 .Lrk_dU_1_2
	v_pk_add_f32 v[126:127], v[126:127], v[240:241]
	v_pk_add_f32 v[128:129], v[128:129], v[242:243]
	s_branch .Lrk_joinU
.Lrk_dU_1_2:
	v_pk_add_f32 v[122:123], v[122:123], v[240:241]
	v_pk_add_f32 v[124:125], v[124:125], v[242:243]
	s_branch .Lrk_joinU
.Lrk_dU_2_4:
	s_cmp_lt_u32 s98, 6
	s_cbranch_scc0 .Lrk_dU_3_4
	v_pk_add_f32 v[110:111], v[110:111], v[240:241]
	v_pk_add_f32 v[112:113], v[112:113], v[242:243]
	s_branch .Lrk_joinU
.Lrk_dU_3_4:
	v_pk_add_f32 v[106:107], v[106:107], v[240:241]
	v_pk_add_f32 v[108:109], v[108:109], v[242:243]
	s_branch .Lrk_joinU
.Lrk_dU_4_8:
	s_cmp_lt_u32 s98, 12
	s_cbranch_scc0 .Lrk_dU_6_8
	s_cmp_lt_u32 s98, 10
	s_cbranch_scc0 .Lrk_dU_5_6
	v_pk_add_f32 v[118:119], v[118:119], v[240:241]
	v_pk_add_f32 v[120:121], v[120:121], v[242:243]
	s_branch .Lrk_joinU
.Lrk_dU_5_6:
	v_pk_add_f32 v[114:115], v[114:115], v[240:241]
	v_pk_add_f32 v[116:117], v[116:117], v[242:243]
	s_branch .Lrk_joinU
.Lrk_dU_6_8:
	s_cmp_lt_u32 s98, 14
	s_cbranch_scc0 .Lrk_dU_7_8
	v_pk_add_f32 v[94:95], v[94:95], v[240:241]
	v_pk_add_f32 v[96:97], v[96:97], v[242:243]
	s_branch .Lrk_joinU
.Lrk_dU_7_8:
	v_pk_add_f32 v[90:91], v[90:91], v[240:241]
	v_pk_add_f32 v[92:93], v[92:93], v[242:243]
	s_branch .Lrk_joinU
.Lrk_dU_8_16:
	s_cmp_lt_u32 s98, 24
	s_cbranch_scc0 .Lrk_dU_12_16
	s_cmp_lt_u32 s98, 20
	s_cbranch_scc0 .Lrk_dU_10_12
	s_cmp_lt_u32 s98, 18
	s_cbranch_scc0 .Lrk_dU_9_10
	v_pk_add_f32 v[102:103], v[102:103], v[240:241]
	v_pk_add_f32 v[104:105], v[104:105], v[242:243]
	s_branch .Lrk_joinU
.Lrk_dU_9_10:
	v_pk_add_f32 v[98:99], v[98:99], v[240:241]
	v_pk_add_f32 v[100:101], v[100:101], v[242:243]
	s_branch .Lrk_joinU
.Lrk_dU_10_12:
	s_cmp_lt_u32 s98, 22
	s_cbranch_scc0 .Lrk_dU_11_12
	v_pk_add_f32 v[78:79], v[78:79], v[240:241]
	v_pk_add_f32 v[80:81], v[80:81], v[242:243]
	s_branch .Lrk_joinU
.Lrk_dU_11_12:
	v_pk_add_f32 v[74:75], v[74:75], v[240:241]
	v_pk_add_f32 v[76:77], v[76:77], v[242:243]
	s_branch .Lrk_joinU
.Lrk_dU_12_16:
	s_cmp_lt_u32 s98, 28
	s_cbranch_scc0 .Lrk_dU_14_16
	s_cmp_lt_u32 s98, 26
	s_cbranch_scc0 .Lrk_dU_13_14
	v_pk_add_f32 v[86:87], v[86:87], v[240:241]
	v_pk_add_f32 v[88:89], v[88:89], v[242:243]
	s_branch .Lrk_joinU
.Lrk_dU_13_14:
	v_pk_add_f32 v[82:83], v[82:83], v[240:241]
	v_pk_add_f32 v[84:85], v[84:85], v[242:243]
	s_branch .Lrk_joinU
.Lrk_dU_14_16:
	s_cmp_lt_u32 s98, 30
	s_cbranch_scc0 .Lrk_dU_15_16
	v_pk_add_f32 v[70:71], v[70:71], v[240:241]
	v_pk_add_f32 v[72:73], v[72:73], v[242:243]
	s_branch .Lrk_joinU
.Lrk_dU_15_16:
	v_pk_add_f32 v[66:67], v[66:67], v[240:241]
	v_pk_add_f32 v[68:69], v[68:69], v[242:243]
	s_branch .Lrk_joinU
.Lrk_joinU:
	s_waitcnt lgkmcnt(0)
	s_barrier
	s_setprio 1
	s_waitcnt lgkmcnt(0)
	v_mfma_f32_16x16x32_bf16 v[62:65], v[130:133], v[162:165], v[62:65]
	v_mfma_f32_16x16x32_bf16 v[58:61], v[138:141], v[162:165], v[58:61]
	v_mfma_f32_16x16x32_bf16 v[54:57], v[130:133], v[170:173], v[54:57]
	v_mfma_f32_16x16x32_bf16 v[50:53], v[138:141], v[170:173], v[50:53]
	v_mfma_f32_16x16x32_bf16 v[38:41], v[130:133], v[196:199], v[38:41]
	v_mfma_f32_16x16x32_bf16 v[34:37], v[138:141], v[196:199], v[34:37]
	v_mfma_f32_16x16x32_bf16 v[22:25], v[130:133], v[204:207], v[22:25]
	v_mfma_f32_16x16x32_bf16 v[18:21], v[138:141], v[204:207], v[18:21]
	v_mfma_f32_16x16x32_bf16 v[62:65], v[134:137], v[166:169], v[62:65]
	v_mfma_f32_16x16x32_bf16 v[58:61], v[142:145], v[166:169], v[58:61]
	v_mfma_f32_16x16x32_bf16 v[54:57], v[134:137], v[174:177], v[54:57]
	v_mfma_f32_16x16x32_bf16 v[50:53], v[142:145], v[174:177], v[50:53]
	v_mfma_f32_16x16x32_bf16 v[38:41], v[134:137], v[200:203], v[38:41]
	v_mfma_f32_16x16x32_bf16 v[34:37], v[142:145], v[200:203], v[34:37]
	v_mfma_f32_16x16x32_bf16 v[22:25], v[134:137], v[208:211], v[22:25]
	v_mfma_f32_16x16x32_bf16 v[18:21], v[142:145], v[208:211], v[18:21]
	s_setprio 0
	s_setprio 1
	v_mfma_f32_16x16x32_bf16 v[46:49], v[146:149], v[162:165], v[46:49]
	v_mfma_f32_16x16x32_bf16 v[42:45], v[154:157], v[162:165], v[42:45]
	v_mfma_f32_16x16x32_bf16 v[30:33], v[146:149], v[170:173], v[30:33]
	v_mfma_f32_16x16x32_bf16 v[26:29], v[154:157], v[170:173], v[26:29]
	v_mfma_f32_16x16x32_bf16 v[14:17], v[146:149], v[196:199], v[14:17]
	v_mfma_f32_16x16x32_bf16 v[10:13], v[154:157], v[196:199], v[10:13]
	v_mfma_f32_16x16x32_bf16 v[6:9], v[146:149], v[204:207], v[6:9]
	v_mfma_f32_16x16x32_bf16 v[2:5], v[154:157], v[204:207], v[2:5]
	v_mfma_f32_16x16x32_bf16 v[46:49], v[150:153], v[166:169], v[46:49]
	v_mfma_f32_16x16x32_bf16 v[42:45], v[158:161], v[166:169], v[42:45]
	v_mfma_f32_16x16x32_bf16 v[30:33], v[150:153], v[174:177], v[30:33]
	v_mfma_f32_16x16x32_bf16 v[26:29], v[158:161], v[174:177], v[26:29]
	v_mfma_f32_16x16x32_bf16 v[14:17], v[150:153], v[200:203], v[14:17]
	v_mfma_f32_16x16x32_bf16 v[10:13], v[158:161], v[200:203], v[10:13]
	v_mfma_f32_16x16x32_bf16 v[6:9], v[150:153], v[208:211], v[6:9]
	v_mfma_f32_16x16x32_bf16 v[2:5], v[158:161], v[208:211], v[2:5]
	s_setprio 0
	s_barrier
	s_add_i32 s68, 0, 0x18000
	v_add_u32_e32 v0, s68, v223
	s_add_i32 s69, 0, 0x1c000
	ds_read_b128 v[130:133], v0
	ds_read_b128 v[134:137], v0 offset:1024
	ds_read_b128 v[138:141], v0 offset:2048
	ds_read_b128 v[142:145], v0 offset:3072
	v_add_u32_e32 v0, s69, v223
	ds_read_b128 v[146:149], v0
	ds_read_b128 v[150:153], v0 offset:1024
	ds_read_b128 v[154:157], v0 offset:2048
	ds_read_b128 v[158:161], v0 offset:3072
	s_add_u32 s50, s50, s90
	s_addc_u32 s51, s51, 0
	s_mov_b32 m0, s65
	s_add_i32 s98, vcc_lo, -2
	s_lshr_b32 s99, s98, 3
	s_lshl_b32 s99, s99, 17
	s_and_b32 vcc_hi, s98, 2
	s_lshl_b32 vcc_hi, vcc_hi, 5
	s_or_b32 s99, s99, vcc_hi
	s_and_b32 vcc_hi, s98, 4
	s_lshl_b32 vcc_hi, vcc_hi, 7
	s_or_b32 s98, s99, vcc_hi
	s_add_u32 s98, s98, 0x100000
	s_add_u32 s98, s100, s98
	s_addc_u32 s99, s101, 0
	s_nop 0
	global_load_dwordx4 v[240:243], v238, s[98:99]
	v_lshl_add_u64 v[236:237], s[50:51], 0, v[184:185]
	ds_read_b128 v[162:165], v226 offset:32768
	ds_read_b128 v[166:169], v226 offset:33792
	ds_read_b128 v[170:173], v226 offset:34816
	ds_read_b128 v[174:177], v226 offset:35840
	ds_read_b128 v[196:199], v226 offset:36864
	ds_read_b128 v[200:203], v226 offset:37888
	ds_read_b128 v[204:207], v226 offset:38912
	ds_read_b128 v[208:211], v226 offset:39936
	global_load_lds_dwordx4 v[236:237], off
	v_lshl_add_u64 v[236:237], s[50:51], 0, v[180:181]
	s_mov_b32 m0, s22
	s_nop 0
	global_load_lds_dwordx4 v[236:237], off
	s_waitcnt vmcnt(9)
	s_waitcnt lgkmcnt(0)
	s_barrier
	s_setprio 1
	s_waitcnt lgkmcnt(0)
	v_mfma_f32_16x16x32_bf16 v[126:129], v[130:133], v[162:165], v[126:129]
	v_mfma_f32_16x16x32_bf16 v[122:125], v[138:141], v[162:165], v[122:125]
	v_mfma_f32_16x16x32_bf16 v[118:121], v[130:133], v[170:173], v[118:121]
	v_mfma_f32_16x16x32_bf16 v[114:117], v[138:141], v[170:173], v[114:117]
	v_mfma_f32_16x16x32_bf16 v[102:105], v[130:133], v[196:199], v[102:105]
	v_mfma_f32_16x16x32_bf16 v[98:101], v[138:141], v[196:199], v[98:101]
	v_mfma_f32_16x16x32_bf16 v[86:89], v[130:133], v[204:207], v[86:89]
	v_mfma_f32_16x16x32_bf16 v[82:85], v[138:141], v[204:207], v[82:85]
	v_mfma_f32_16x16x32_bf16 v[126:129], v[134:137], v[166:169], v[126:129]
	v_mfma_f32_16x16x32_bf16 v[122:125], v[142:145], v[166:169], v[122:125]
	v_mfma_f32_16x16x32_bf16 v[118:121], v[134:137], v[174:177], v[118:121]
	v_mfma_f32_16x16x32_bf16 v[114:117], v[142:145], v[174:177], v[114:117]
	v_mfma_f32_16x16x32_bf16 v[102:105], v[134:137], v[200:203], v[102:105]
	v_mfma_f32_16x16x32_bf16 v[98:101], v[142:145], v[200:203], v[98:101]
	v_mfma_f32_16x16x32_bf16 v[86:89], v[134:137], v[208:211], v[86:89]
	v_mfma_f32_16x16x32_bf16 v[82:85], v[142:145], v[208:211], v[82:85]
	s_setprio 0
	s_setprio 1
	v_mfma_f32_16x16x32_bf16 v[110:113], v[146:149], v[162:165], v[110:113]
	v_mfma_f32_16x16x32_bf16 v[106:109], v[154:157], v[162:165], v[106:109]
	v_mfma_f32_16x16x32_bf16 v[94:97], v[146:149], v[170:173], v[94:97]
	v_mfma_f32_16x16x32_bf16 v[90:93], v[154:157], v[170:173], v[90:93]
	v_mfma_f32_16x16x32_bf16 v[78:81], v[146:149], v[196:199], v[78:81]
	v_mfma_f32_16x16x32_bf16 v[74:77], v[154:157], v[196:199], v[74:77]
	v_mfma_f32_16x16x32_bf16 v[70:73], v[146:149], v[204:207], v[70:73]
	v_mfma_f32_16x16x32_bf16 v[66:69], v[154:157], v[204:207], v[66:69]
	v_mfma_f32_16x16x32_bf16 v[110:113], v[150:153], v[166:169], v[110:113]
	v_mfma_f32_16x16x32_bf16 v[106:109], v[158:161], v[166:169], v[106:109]
	v_mfma_f32_16x16x32_bf16 v[94:97], v[150:153], v[174:177], v[94:97]
	v_mfma_f32_16x16x32_bf16 v[90:93], v[158:161], v[174:177], v[90:93]
	v_mfma_f32_16x16x32_bf16 v[78:81], v[150:153], v[200:203], v[78:81]
	v_mfma_f32_16x16x32_bf16 v[74:77], v[158:161], v[200:203], v[74:77]
	v_mfma_f32_16x16x32_bf16 v[70:73], v[150:153], v[208:211], v[70:73]
	v_mfma_f32_16x16x32_bf16 v[66:69], v[158:161], v[208:211], v[66:69]
	s_setprio 0
	s_barrier
	s_add_i32 s50, s68, s63
	v_lshl_add_u64 v[212:213], v[212:213], 0, s[94:95]
	s_mov_b32 m0, s50
	ds_read_b128 v[162:165], v226 offset:49152
	ds_read_b128 v[166:169], v226 offset:50176
	ds_read_b128 v[170:173], v226 offset:51200
	ds_read_b128 v[174:177], v226 offset:52224
	ds_read_b128 v[196:199], v226 offset:53248
	ds_read_b128 v[200:203], v226 offset:54272
	ds_read_b128 v[204:207], v226 offset:55296
	ds_read_b128 v[208:211], v226 offset:56320
	global_load_lds_dwordx4 v[212:213], off
	v_lshl_add_u64 v[212:213], v[214:215], 0, s[94:95]
	s_add_i32 m0, s50, 0x2000
	s_add_i32 s50, s69, s63
	global_load_lds_dwordx4 v[212:213], off
	v_lshl_add_u64 v[212:213], v[216:217], 0, s[94:95]
	s_mov_b32 m0, s50
	s_nop 0
	global_load_lds_dwordx4 v[212:213], off
	v_lshl_add_u64 v[212:213], v[218:219], 0, s[94:95]
	s_add_i32 m0, s50, 0x2000
	s_nop 0
	global_load_lds_dwordx4 v[212:213], off
	v_lshl_add_u64 v[212:213], v[232:233], 0, s[94:95]
	s_mov_b32 m0, s87
	s_nop 0
	global_load_lds_dwordx4 v[212:213], off
	v_lshl_add_u64 v[212:213], v[234:235], 0, s[94:95]
	s_mov_b32 m0, s2
	s_nop 0
	global_load_lds_dwordx4 v[212:213], off
	s_waitcnt vmcnt(8)
	s_add_i32 s98, vcc_lo, -2
	s_cmp_lt_u32 s98, 16
	s_cbranch_scc0 .Lrk_dL_8_16
	s_cmp_lt_u32 s98, 8
	s_cbranch_scc0 .Lrk_dL_4_8
	s_cmp_lt_u32 s98, 4
	s_cbranch_scc0 .Lrk_dL_2_4
	s_cmp_lt_u32 s98, 2
	s_cbranch_scc0 .Lrk_dL_1_2
	v_pk_add_f32 v[62:63], v[62:63], v[240:241]
	v_pk_add_f32 v[64:65], v[64:65], v[242:243]
	s_branch .Lrk_joinL
.Lrk_dL_1_2:
	v_pk_add_f32 v[58:59], v[58:59], v[240:241]
	v_pk_add_f32 v[60:61], v[60:61], v[242:243]
	s_branch .Lrk_joinL
.Lrk_dL_2_4:
	s_cmp_lt_u32 s98, 6
	s_cbranch_scc0 .Lrk_dL_3_4
	v_pk_add_f32 v[46:47], v[46:47], v[240:241]
	v_pk_add_f32 v[48:49], v[48:49], v[242:243]
	s_branch .Lrk_joinL
.Lrk_dL_3_4:
	v_pk_add_f32 v[42:43], v[42:43], v[240:241]
	v_pk_add_f32 v[44:45], v[44:45], v[242:243]
	s_branch .Lrk_joinL
.Lrk_dL_4_8:
	s_cmp_lt_u32 s98, 12
	s_cbranch_scc0 .Lrk_dL_6_8
	s_cmp_lt_u32 s98, 10
	s_cbranch_scc0 .Lrk_dL_5_6
	v_pk_add_f32 v[54:55], v[54:55], v[240:241]
	v_pk_add_f32 v[56:57], v[56:57], v[242:243]
	s_branch .Lrk_joinL
.Lrk_dL_5_6:
	v_pk_add_f32 v[50:51], v[50:51], v[240:241]
	v_pk_add_f32 v[52:53], v[52:53], v[242:243]
	s_branch .Lrk_joinL
.Lrk_dL_6_8:
	s_cmp_lt_u32 s98, 14
	s_cbranch_scc0 .Lrk_dL_7_8
	v_pk_add_f32 v[30:31], v[30:31], v[240:241]
	v_pk_add_f32 v[32:33], v[32:33], v[242:243]
	s_branch .Lrk_joinL
.Lrk_dL_7_8:
	v_pk_add_f32 v[26:27], v[26:27], v[240:241]
	v_pk_add_f32 v[28:29], v[28:29], v[242:243]
	s_branch .Lrk_joinL
.Lrk_dL_8_16:
	s_cmp_lt_u32 s98, 24
	s_cbranch_scc0 .Lrk_dL_12_16
	s_cmp_lt_u32 s98, 20
	s_cbranch_scc0 .Lrk_dL_10_12
	s_cmp_lt_u32 s98, 18
	s_cbranch_scc0 .Lrk_dL_9_10
	v_pk_add_f32 v[38:39], v[38:39], v[240:241]
	v_pk_add_f32 v[40:41], v[40:41], v[242:243]
	s_branch .Lrk_joinL
.Lrk_dL_9_10:
	v_pk_add_f32 v[34:35], v[34:35], v[240:241]
	v_pk_add_f32 v[36:37], v[36:37], v[242:243]
	s_branch .Lrk_joinL
.Lrk_dL_10_12:
	s_cmp_lt_u32 s98, 22
	s_cbranch_scc0 .Lrk_dL_11_12
	v_pk_add_f32 v[14:15], v[14:15], v[240:241]
	v_pk_add_f32 v[16:17], v[16:17], v[242:243]
	s_branch .Lrk_joinL
.Lrk_dL_11_12:
	v_pk_add_f32 v[10:11], v[10:11], v[240:241]
	v_pk_add_f32 v[12:13], v[12:13], v[242:243]
	s_branch .Lrk_joinL
.Lrk_dL_12_16:
	s_cmp_lt_u32 s98, 28
	s_cbranch_scc0 .Lrk_dL_14_16
	s_cmp_lt_u32 s98, 26
	s_cbranch_scc0 .Lrk_dL_13_14
	v_pk_add_f32 v[22:23], v[22:23], v[240:241]
	v_pk_add_f32 v[24:25], v[24:25], v[242:243]
	s_branch .Lrk_joinL
.Lrk_dL_13_14:
	v_pk_add_f32 v[18:19], v[18:19], v[240:241]
	v_pk_add_f32 v[20:21], v[20:21], v[242:243]
	s_branch .Lrk_joinL
.Lrk_dL_14_16:
	s_cmp_lt_u32 s98, 30
	s_cbranch_scc0 .Lrk_dL_15_16
	v_pk_add_f32 v[6:7], v[6:7], v[240:241]
	v_pk_add_f32 v[8:9], v[8:9], v[242:243]
	s_branch .Lrk_joinL
.Lrk_dL_15_16:
	v_pk_add_f32 v[2:3], v[2:3], v[240:241]
	v_pk_add_f32 v[4:5], v[4:5], v[242:243]
	s_branch .Lrk_joinL
.Lrk_joinL:
	s_waitcnt lgkmcnt(0)
	s_barrier
	s_setprio 1
	s_waitcnt lgkmcnt(0)
	v_mfma_f32_16x16x32_bf16 v[62:65], v[130:133], v[162:165], v[62:65]
	v_mfma_f32_16x16x32_bf16 v[58:61], v[138:141], v[162:165], v[58:61]
	v_mfma_f32_16x16x32_bf16 v[54:57], v[130:133], v[170:173], v[54:57]
	v_mfma_f32_16x16x32_bf16 v[50:53], v[138:141], v[170:173], v[50:53]
	v_mfma_f32_16x16x32_bf16 v[38:41], v[130:133], v[196:199], v[38:41]
	v_mfma_f32_16x16x32_bf16 v[34:37], v[138:141], v[196:199], v[34:37]
	v_mfma_f32_16x16x32_bf16 v[22:25], v[130:133], v[204:207], v[22:25]
	v_mfma_f32_16x16x32_bf16 v[18:21], v[138:141], v[204:207], v[18:21]
	v_mfma_f32_16x16x32_bf16 v[62:65], v[134:137], v[166:169], v[62:65]
	v_mfma_f32_16x16x32_bf16 v[58:61], v[142:145], v[166:169], v[58:61]
	v_mfma_f32_16x16x32_bf16 v[54:57], v[134:137], v[174:177], v[54:57]
	v_mfma_f32_16x16x32_bf16 v[50:53], v[142:145], v[174:177], v[50:53]
	v_mfma_f32_16x16x32_bf16 v[38:41], v[134:137], v[200:203], v[38:41]
	v_mfma_f32_16x16x32_bf16 v[34:37], v[142:145], v[200:203], v[34:37]
	v_mfma_f32_16x16x32_bf16 v[22:25], v[134:137], v[208:211], v[22:25]
	v_mfma_f32_16x16x32_bf16 v[18:21], v[142:145], v[208:211], v[18:21]
	s_setprio 0
	s_setprio 1
	v_mfma_f32_16x16x32_bf16 v[46:49], v[146:149], v[162:165], v[46:49]
	v_mfma_f32_16x16x32_bf16 v[42:45], v[154:157], v[162:165], v[42:45]
	v_mfma_f32_16x16x32_bf16 v[30:33], v[146:149], v[170:173], v[30:33]
	v_mfma_f32_16x16x32_bf16 v[26:29], v[154:157], v[170:173], v[26:29]
	v_mfma_f32_16x16x32_bf16 v[14:17], v[146:149], v[196:199], v[14:17]
	v_mfma_f32_16x16x32_bf16 v[10:13], v[154:157], v[196:199], v[10:13]
	v_mfma_f32_16x16x32_bf16 v[6:9], v[146:149], v[204:207], v[6:9]
	v_mfma_f32_16x16x32_bf16 v[2:5], v[154:157], v[204:207], v[2:5]
	v_mfma_f32_16x16x32_bf16 v[46:49], v[150:153], v[166:169], v[46:49]
	v_mfma_f32_16x16x32_bf16 v[42:45], v[158:161], v[166:169], v[42:45]
	v_mfma_f32_16x16x32_bf16 v[30:33], v[150:153], v[174:177], v[30:33]
	v_mfma_f32_16x16x32_bf16 v[26:29], v[158:161], v[174:177], v[26:29]
	v_mfma_f32_16x16x32_bf16 v[14:17], v[150:153], v[200:203], v[14:17]
	v_mfma_f32_16x16x32_bf16 v[10:13], v[158:161], v[200:203], v[10:13]
	v_mfma_f32_16x16x32_bf16 v[6:9], v[150:153], v[208:211], v[6:9]
	v_mfma_f32_16x16x32_bf16 v[2:5], v[158:161], v[208:211], v[2:5]
	s_setprio 0
	s_barrier
	s_add_u32 s48, s48, 0x100
	s_addc_u32 s49, s49, 0
	s_add_u32 s56, s56, 0x100
	s_addc_u32 s57, s57, 0
	s_cmp_ge_i32 vcc_lo, s55
	s_mov_b32 s50, vcc_lo
	s_cbranch_scc1 .Lrk_done
	s_cmp_lt_u32 vcc_lo, 32
	s_cbranch_scc1 .Lrk_344
	s_branch .LBB0_344
.Lrk_store:
	v_ashrrev_i32_e32 v197, 31, v196
	v_lshlrev_b64 v[130:131], 13, v[196:197]
	v_lshl_add_u64 v[130:131], s[78:79], 0, v[130:131]
	v_lshlrev_b64 v[206:207], 2, v[202:203]
	v_lshl_add_u64 v[134:135], v[130:131], 0, v[206:207]
	global_store_dwordx4 v[134:135], v[126:129], off
	global_store_dwordx4 v[134:135], v[122:125], off offset:64
	global_store_dwordx4 v[134:135], v[110:113], off offset:512
	global_store_dwordx4 v[134:135], v[106:109], off offset:576
	s_mov_b32 s98, 0x20000
	s_mov_b32 s99, 0
	v_lshl_add_u64 v[136:137], v[134:135], 0, s[98:99]
	global_store_dwordx4 v[136:137], v[118:121], off
	global_store_dwordx4 v[136:137], v[114:117], off offset:64
	global_store_dwordx4 v[136:137], v[94:97], off offset:512
	global_store_dwordx4 v[136:137], v[90:93], off offset:576
	s_mov_b32 s98, 0x40000
	s_mov_b32 s99, 0
	v_lshl_add_u64 v[136:137], v[134:135], 0, s[98:99]
	global_store_dwordx4 v[136:137], v[102:105], off
	global_store_dwordx4 v[136:137], v[98:101], off offset:64
	global_store_dwordx4 v[136:137], v[78:81], off offset:512
	global_store_dwordx4 v[136:137], v[74:77], off offset:576
	s_mov_b32 s98, 0x60000
	s_mov_b32 s99, 0
	v_lshl_add_u64 v[136:137], v[134:135], 0, s[98:99]
	global_store_dwordx4 v[136:137], v[86:89], off
	global_store_dwordx4 v[136:137], v[82:85], off offset:64
	global_store_dwordx4 v[136:137], v[70:73], off offset:512
	global_store_dwordx4 v[136:137], v[66:69], off offset:576
	s_mov_b32 s98, 0x100000
	s_mov_b32 s99, 0
	v_lshl_add_u64 v[136:137], v[134:135], 0, s[98:99]
	global_store_dwordx4 v[136:137], v[62:65], off
	global_store_dwordx4 v[136:137], v[58:61], off offset:64
	global_store_dwordx4 v[136:137], v[46:49], off offset:512
	global_store_dwordx4 v[136:137], v[42:45], off offset:576
	s_mov_b32 s98, 0x120000
	s_mov_b32 s99, 0
	v_lshl_add_u64 v[136:137], v[134:135], 0, s[98:99]
	global_store_dwordx4 v[136:137], v[54:57], off
	global_store_dwordx4 v[136:137], v[50:53], off offset:64
	global_store_dwordx4 v[136:137], v[30:33], off offset:512
	global_store_dwordx4 v[136:137], v[26:29], off offset:576
	s_mov_b32 s98, 0x140000
	s_mov_b32 s99, 0
	v_lshl_add_u64 v[136:137], v[134:135], 0, s[98:99]
	global_store_dwordx4 v[136:137], v[38:41], off
	global_store_dwordx4 v[136:137], v[34:37], off offset:64
	global_store_dwordx4 v[136:137], v[14:17], off offset:512
	global_store_dwordx4 v[136:137], v[10:13], off offset:576
	s_mov_b32 s98, 0x160000
	s_mov_b32 s99, 0
	v_lshl_add_u64 v[136:137], v[134:135], 0, s[98:99]
	global_store_dwordx4 v[136:137], v[22:25], off
	global_store_dwordx4 v[136:137], v[18:21], off offset:64
	global_store_dwordx4 v[136:137], v[6:9], off offset:512
	global_store_dwordx4 v[136:137], v[2:5], off offset:576
	s_mov_b64 s[48:49], 0
	s_branch .LBB0_385

.LBB0_343:
	s_add_i32 s15, s55, -2
	s_add_u32 s48, s48, 0x80
	s_addc_u32 s49, s49, 0
	s_add_u32 s56, s50, 0x100
	v_mov_b32_e32 v2, 0
	s_addc_u32 s57, s51, 0
	s_mov_b32 s50, 0
	v_mov_b32_e32 v3, v2
	v_mov_b32_e32 v4, v2
	v_mov_b32_e32 v5, v2
	v_mov_b32_e32 v6, v2
	v_mov_b32_e32 v7, v2
	v_mov_b32_e32 v8, v2
	v_mov_b32_e32 v9, v2
	v_mov_b32_e32 v10, v2
	v_mov_b32_e32 v11, v2
	v_mov_b32_e32 v12, v2
	v_mov_b32_e32 v13, v2
	v_mov_b32_e32 v14, v2
	v_mov_b32_e32 v15, v2
	v_mov_b32_e32 v16, v2
	v_mov_b32_e32 v17, v2
	v_mov_b32_e32 v26, v2
	v_mov_b32_e32 v27, v2
	v_mov_b32_e32 v28, v2
	v_mov_b32_e32 v29, v2
	v_mov_b32_e32 v30, v2
	v_mov_b32_e32 v31, v2
	v_mov_b32_e32 v32, v2
	v_mov_b32_e32 v33, v2
	v_mov_b32_e32 v42, v2
	v_mov_b32_e32 v43, v2
	v_mov_b32_e32 v44, v2
	v_mov_b32_e32 v45, v2
	v_mov_b32_e32 v46, v2
	v_mov_b32_e32 v47, v2
	v_mov_b32_e32 v48, v2
	v_mov_b32_e32 v49, v2
	v_mov_b32_e32 v18, v2
	v_mov_b32_e32 v19, v2
	v_mov_b32_e32 v20, v2
	v_mov_b32_e32 v21, v2
	v_mov_b32_e32 v22, v2
	v_mov_b32_e32 v23, v2
	v_mov_b32_e32 v24, v2
	v_mov_b32_e32 v25, v2
	v_mov_b32_e32 v34, v2
	v_mov_b32_e32 v35, v2
	v_mov_b32_e32 v36, v2
	v_mov_b32_e32 v37, v2
	v_mov_b32_e32 v38, v2
	v_mov_b32_e32 v39, v2
	v_mov_b32_e32 v40, v2
	v_mov_b32_e32 v41, v2
	v_mov_b32_e32 v50, v2
	v_mov_b32_e32 v51, v2
	v_mov_b32_e32 v52, v2
	v_mov_b32_e32 v53, v2
	v_mov_b32_e32 v54, v2
	v_mov_b32_e32 v55, v2
	v_mov_b32_e32 v56, v2
	v_mov_b32_e32 v57, v2
	v_mov_b32_e32 v58, v2
	v_mov_b32_e32 v59, v2
	v_mov_b32_e32 v60, v2
	v_mov_b32_e32 v61, v2
	v_mov_b32_e32 v62, v2
	v_mov_b32_e32 v63, v2
	v_mov_b32_e32 v64, v2
	v_mov_b32_e32 v65, v2
	v_mov_b32_e32 v66, v2
	v_mov_b32_e32 v67, v2
	v_mov_b32_e32 v68, v2
	v_mov_b32_e32 v69, v2
	v_mov_b32_e32 v70, v2
	v_mov_b32_e32 v71, v2
	v_mov_b32_e32 v72, v2
	v_mov_b32_e32 v73, v2
	v_mov_b32_e32 v74, v2
	v_mov_b32_e32 v75, v2
	v_mov_b32_e32 v76, v2
	v_mov_b32_e32 v77, v2
	v_mov_b32_e32 v78, v2
	v_mov_b32_e32 v79, v2
	v_mov_b32_e32 v80, v2
	v_mov_b32_e32 v81, v2
	v_mov_b32_e32 v90, v2
	v_mov_b32_e32 v91, v2
	v_mov_b32_e32 v92, v2
	v_mov_b32_e32 v93, v2
	v_mov_b32_e32 v94, v2
	v_mov_b32_e32 v95, v2
	v_mov_b32_e32 v96, v2
	v_mov_b32_e32 v97, v2
	v_mov_b32_e32 v106, v2
	v_mov_b32_e32 v107, v2
	v_mov_b32_e32 v108, v2
	v_mov_b32_e32 v109, v2
	v_mov_b32_e32 v110, v2
	v_mov_b32_e32 v111, v2
	v_mov_b32_e32 v112, v2
	v_mov_b32_e32 v113, v2
	v_mov_b32_e32 v82, v2
	v_mov_b32_e32 v83, v2
	v_mov_b32_e32 v84, v2
	v_mov_b32_e32 v85, v2
	v_mov_b32_e32 v86, v2
	v_mov_b32_e32 v87, v2
	v_mov_b32_e32 v88, v2
	v_mov_b32_e32 v89, v2
	v_mov_b32_e32 v98, v2
	v_mov_b32_e32 v99, v2
	v_mov_b32_e32 v100, v2
	v_mov_b32_e32 v101, v2
	v_mov_b32_e32 v102, v2
	v_mov_b32_e32 v103, v2
	v_mov_b32_e32 v104, v2
	v_mov_b32_e32 v105, v2
	v_mov_b32_e32 v114, v2
	v_mov_b32_e32 v115, v2
	v_mov_b32_e32 v116, v2
	v_mov_b32_e32 v117, v2
	v_mov_b32_e32 v118, v2
	v_mov_b32_e32 v119, v2
	v_mov_b32_e32 v120, v2
	v_mov_b32_e32 v121, v2
	v_mov_b32_e32 v122, v2
	v_mov_b32_e32 v123, v2
	v_mov_b32_e32 v124, v2
	v_mov_b32_e32 v125, v2
	v_mov_b32_e32 v126, v2
	v_mov_b32_e32 v127, v2
	v_mov_b32_e32 v128, v2
	v_mov_b32_e32 v129, v2
	s_cmp_eq_u32 s58, 2
	s_cbranch_scc0 .LBB0_344
	s_cmp_lt_i32 s88, 0
	s_cbranch_scc0 .LBB0_344
	s_cmp_lt_i32 s55, 32
	s_cbranch_scc1 .LBB0_344
	v_or_b32_e32 v238, s86, v188
	v_lshlrev_b32_e32 v238, 13, v238
	v_lshl_add_u32 v238, v225, 2, v238
	s_lshl_b32 s98, s54, 21
	s_lshl_b32 s99, s23, 10
	s_add_u32 s98, s98, s99
	s_add_u32 s100, s18, s98
	s_addc_u32 s101, s19, 0
	s_branch .Lrk_344

.LBB0_374:
	s_and_b64 vcc, exec, s[48:49]
	s_cbranch_vccz .LBB0_387
	v_lshl_or_b32 v202, s23, 8, v225
	s_cmp_lt_i32 s88, 0
	s_mov_b64 s[48:49], -1
	v_ashrrev_i32_e32 v203, 31, v202
	v_add_u32_e32 v204, 0xffffe000, v196
	v_add_u32_e32 v200, 0xffffe010, v196
	v_add_u32_e32 v198, 0xffffe020, v196
	s_cbranch_scc0 .LBB0_385
	s_cmp_lt_i32 s55, 32
	s_cbranch_scc0 .Lrk_store
	s_movk_i32 s15, 0x2000
	v_ashrrev_i32_e32 v197, 31, v196
	v_cmp_gt_i32_e32 vcc, s15, v196
	v_mov_b32_e32 v0, s77
	v_mov_b32_e32 v134, s19
	v_cndmask_b32_e32 v131, 0, v197, vcc
	v_cndmask_b32_e32 v130, v204, v196, vcc
	v_mov_b32_e32 v135, s76
	v_mov_b32_e32 v136, s18
	v_cndmask_b32_e32 v133, v0, v134, vcc
	v_cndmask_b32_e32 v132, v135, v136, vcc
	v_lshlrev_b64 v[130:131], 13, v[130:131]
	v_lshl_add_u64 v[130:131], v[132:133], 0, v[130:131]
	v_lshlrev_b64 v[206:207], 2, v[202:203]
	v_or_b32_e32 v212, 16, v196
	v_lshl_add_u64 v[130:131], v[130:131], 0, v[206:207]
	v_ashrrev_i32_e32 v213, 31, v212
	v_cmp_gt_i32_e32 vcc, s15, v212
	global_load_dwordx4 v[174:177], v[130:131], off
	global_load_dwordx4 v[170:173], v[130:131], off offset:64
	global_load_dwordx4 v[166:169], v[130:131], off offset:512
	global_load_dwordx4 v[162:165], v[130:131], off offset:576
	v_cndmask_b32_e32 v131, 0, v213, vcc
	v_cndmask_b32_e32 v130, v200, v212, vcc
	v_cndmask_b32_e32 v133, v0, v134, vcc
	v_cndmask_b32_e32 v132, v135, v136, vcc
	v_lshlrev_b64 v[130:131], 13, v[130:131]
	v_lshl_add_u64 v[130:131], v[132:133], 0, v[130:131]
	v_or_b32_e32 v210, 32, v196
	v_lshl_add_u64 v[130:131], v[130:131], 0, v[206:207]
	v_ashrrev_i32_e32 v211, 31, v210
	v_cmp_gt_i32_e32 vcc, s15, v210
	global_load_dwordx4 v[158:161], v[130:131], off
	global_load_dwordx4 v[154:157], v[130:131], off offset:64
	global_load_dwordx4 v[150:153], v[130:131], off offset:512
	global_load_dwordx4 v[146:149], v[130:131], off offset:576
	v_cndmask_b32_e32 v131, 0, v211, vcc
	v_cndmask_b32_e32 v130, v198, v210, vcc
	v_cndmask_b32_e32 v133, v0, v134, vcc
	v_cndmask_b32_e32 v132, v135, v136, vcc
	v_lshlrev_b64 v[130:131], 13, v[130:131]
	v_lshl_add_u64 v[130:131], v[132:133], 0, v[130:131]
	v_lshl_add_u64 v[130:131], v[130:131], 0, v[206:207]
	global_load_dwordx4 v[142:145], v[130:131], off
	global_load_dwordx4 v[138:141], v[130:131], off offset:64
	global_load_dwordx4 v[134:137], v[130:131], off offset:512
	s_nop 0
	global_load_dwordx4 v[130:133], v[130:131], off offset:576
	v_or_b32_e32 v214, 48, v196
	s_movk_i32 s15, 0x1fff
	v_cmp_lt_i32_e32 vcc, s15, v214
	s_and_saveexec_b64 s[48:49], vcc
	s_xor_b64 s[48:49], exec, s[48:49]
	v_add_u32_e32 v0, 0xffffe030, v196
	v_lshlrev_b64 v[208:209], 13, v[0:1]
	v_mov_b32_e32 v215, v1
	v_lshl_add_u64 v[216:217], s[76:77], 0, v[208:209]
	v_lshlrev_b64 v[208:209], 13, v[214:215]
	s_andn2_saveexec_b64 s[48:49], s[48:49]
	v_ashrrev_i32_e32 v215, 31, v214
	v_lshlrev_b64 v[208:209], 13, v[214:215]
	v_lshl_add_u64 v[216:217], s[18:19], 0, v[208:209]
	s_or_b64 exec, exec, s[48:49]
	v_lshl_add_u64 v[218:219], v[216:217], 0, v[206:207]
	global_load_dwordx4 v[214:217], v[218:219], off
	global_load_dwordx4 v[232:235], v[218:219], off offset:64
	global_load_dwordx4 v[236:239], v[218:219], off offset:512
	global_load_dwordx4 v[240:243], v[218:219], off offset:576
	v_lshlrev_b64 v[218:219], 13, v[196:197]
	v_lshl_add_u64 v[218:219], s[78:79], 0, v[218:219]
	v_lshl_add_u64 v[218:219], v[218:219], 0, v[206:207]
	s_waitcnt vmcnt(0)
	v_pk_add_f32 v[164:165], v[108:109], v[164:165]
	v_pk_add_f32 v[162:163], v[106:107], v[162:163]
	global_store_dwordx4 v[218:219], v[162:165], off offset:576
	v_pk_add_f32 v[148:149], v[92:93], v[148:149]
	v_pk_add_f32 v[146:147], v[90:91], v[146:147]
	v_lshlrev_b64 v[162:163], 13, v[212:213]
	v_lshl_add_u64 v[162:163], s[78:79], 0, v[162:163]
	v_lshl_add_u64 v[162:163], v[162:163], 0, v[206:207]
	global_store_dwordx4 v[162:163], v[146:149], off offset:576
	v_pk_add_f32 v[132:133], v[76:77], v[132:133]
	v_pk_add_f32 v[130:131], v[74:75], v[130:131]
	v_lshlrev_b64 v[146:147], 13, v[210:211]
	v_lshl_add_u64 v[146:147], s[78:79], 0, v[146:147]
	v_lshl_add_u64 v[146:147], v[146:147], 0, v[206:207]
	v_pk_add_f32 v[136:137], v[80:81], v[136:137]
	v_pk_add_f32 v[134:135], v[78:79], v[134:135]
	global_store_dwordx4 v[146:147], v[130:133], off offset:576
	v_pk_add_f32 v[176:177], v[176:177], v[128:129]
	v_pk_add_f32 v[174:175], v[174:175], v[126:127]
	v_lshl_add_u64 v[130:131], s[78:79], 0, v[208:209]
	v_pk_add_f32 v[172:173], v[172:173], v[124:125]
	v_pk_add_f32 v[170:171], v[170:171], v[122:123]
	v_pk_add_f32 v[168:169], v[112:113], v[168:169]
	v_pk_add_f32 v[166:167], v[110:111], v[166:167]
	v_pk_add_f32 v[160:161], v[160:161], v[120:121]
	v_pk_add_f32 v[158:159], v[158:159], v[118:119]
	v_pk_add_f32 v[156:157], v[156:157], v[116:117]
	v_pk_add_f32 v[154:155], v[154:155], v[114:115]
	v_pk_add_f32 v[152:153], v[96:97], v[152:153]
	v_pk_add_f32 v[150:151], v[94:95], v[150:151]
	v_pk_add_f32 v[144:145], v[144:145], v[104:105]
	v_pk_add_f32 v[142:143], v[142:143], v[102:103]
	v_pk_add_f32 v[140:141], v[140:141], v[100:101]
	v_pk_add_f32 v[138:139], v[138:139], v[98:99]
	global_store_dwordx4 v[146:147], v[134:137], off offset:512
	global_store_dwordx4 v[218:219], v[174:177], off
	global_store_dwordx4 v[218:219], v[170:173], off offset:64
	v_lshl_add_u64 v[134:135], v[130:131], 0, v[206:207]
	global_store_dwordx4 v[218:219], v[166:169], off offset:512
	global_store_dwordx4 v[162:163], v[158:161], off
	global_store_dwordx4 v[162:163], v[154:157], off offset:64
	global_store_dwordx4 v[162:163], v[150:153], off offset:512
	global_store_dwordx4 v[146:147], v[142:145], off
	global_store_dwordx4 v[146:147], v[138:141], off offset:64
	s_movk_i32 s15, 0x1f80
	v_add_u32_e32 v208, 0x80, v196
	v_cmp_gt_i32_e32 vcc, s15, v196
	v_add_u32_e32 v0, 0xffffe080, v196
	v_ashrrev_i32_e32 v209, 31, v208
	v_mov_b32_e32 v150, s19
	v_mov_b32_e32 v151, s76
	v_mov_b32_e32 v152, s18
	v_add_u32_e32 v210, 0x90, v196
	s_movk_i32 s15, 0x1f70
	v_ashrrev_i32_e32 v211, 31, v210
	v_add_u32_e32 v146, 0xffffe090, v196
	v_pk_add_f32 v[132:133], v[88:89], v[216:217]
	v_pk_add_f32 v[130:131], v[86:87], v[214:215]
	global_store_dwordx4 v[134:135], v[130:133], off
	v_add_u32_e32 v214, 0xa0, v196
	v_ashrrev_i32_e32 v215, 31, v214
	v_pk_add_f32 v[132:133], v[84:85], v[234:235]
	v_pk_add_f32 v[130:131], v[82:83], v[232:233]
	global_store_dwordx4 v[134:135], v[130:133], off offset:64
	v_add_u32_e32 v216, 0xb0, v196
	s_nop 0
	v_pk_add_f32 v[132:133], v[72:73], v[238:239]
	v_pk_add_f32 v[130:131], v[70:71], v[236:237]
	global_store_dwordx4 v[134:135], v[130:133], off offset:512
	s_nop 1
	v_pk_add_f32 v[132:133], v[68:69], v[242:243]
	v_pk_add_f32 v[130:131], v[66:67], v[240:241]
	global_store_dwordx4 v[134:135], v[130:133], off offset:576
	s_nop 1
	v_cndmask_b32_e32 v130, v0, v208, vcc
	v_mov_b32_e32 v0, s77
	v_cndmask_b32_e32 v131, 0, v209, vcc
	v_cndmask_b32_e32 v133, v0, v150, vcc
	v_cndmask_b32_e32 v132, v151, v152, vcc
	v_cmp_gt_i32_e32 vcc, s15, v196
	v_lshlrev_b64 v[130:131], 13, v[130:131]
	v_lshl_add_u64 v[130:131], v[132:133], 0, v[130:131]
	v_cndmask_b32_e32 v147, 0, v211, vcc
	v_cndmask_b32_e32 v146, v146, v210, vcc
	v_cndmask_b32_e32 v149, v0, v150, vcc
	v_cndmask_b32_e32 v148, v151, v152, vcc
	v_lshlrev_b64 v[146:147], 13, v[146:147]
	v_lshl_add_u64 v[146:147], v[148:149], 0, v[146:147]
	v_lshl_add_u64 v[130:131], v[130:131], 0, v[206:207]
	v_lshl_add_u64 v[146:147], v[146:147], 0, v[206:207]
	s_movk_i32 s15, 0x1f60
	global_load_dwordx4 v[142:145], v[130:131], off
	global_load_dwordx4 v[138:141], v[130:131], off offset:64
	global_load_dwordx4 v[134:137], v[130:131], off offset:512
	s_nop 0
	global_load_dwordx4 v[130:133], v[130:131], off offset:576
	s_nop 0
	global_load_dwordx4 v[174:177], v[146:147], off
	global_load_dwordx4 v[170:173], v[146:147], off offset:64
	global_load_dwordx4 v[162:165], v[146:147], off offset:512
	global_load_dwordx4 v[154:157], v[146:147], off offset:576
	v_cmp_gt_i32_e32 vcc, s15, v196
	v_add_u32_e32 v146, 0xffffe0a0, v196
	s_movk_i32 s15, 0x1f4f
	v_cndmask_b32_e32 v147, 0, v215, vcc
	v_cndmask_b32_e32 v146, v146, v214, vcc
	v_cndmask_b32_e32 v149, v0, v150, vcc
	v_cndmask_b32_e32 v148, v151, v152, vcc
	v_lshlrev_b64 v[146:147], 13, v[146:147]
	v_lshl_add_u64 v[146:147], v[148:149], 0, v[146:147]
	v_lshl_add_u64 v[146:147], v[146:147], 0, v[206:207]
	global_load_dwordx4 v[166:169], v[146:147], off
	global_load_dwordx4 v[158:161], v[146:147], off offset:64
	global_load_dwordx4 v[150:153], v[146:147], off offset:512
	s_nop 0
	global_load_dwordx4 v[146:149], v[146:147], off offset:576
	v_cmp_lt_i32_e32 vcc, s15, v196
	s_and_saveexec_b64 s[48:49], vcc
	s_xor_b64 s[48:49], exec, s[48:49]
	v_add_u32_e32 v0, 0xffffe0b0, v196
	v_lshlrev_b64 v[212:213], 13, v[0:1]
	v_mov_b32_e32 v217, v1
	v_lshl_add_u64 v[218:219], s[76:77], 0, v[212:213]
	v_lshlrev_b64 v[212:213], 13, v[216:217]
	s_andn2_saveexec_b64 s[48:49], s[48:49]
	v_ashrrev_i32_e32 v217, 31, v216
	v_lshlrev_b64 v[212:213], 13, v[216:217]
	v_lshl_add_u64 v[218:219], s[18:19], 0, v[212:213]
	s_or_b64 exec, exec, s[48:49]
	v_lshl_add_u64 v[240:241], v[218:219], 0, v[206:207]
	global_load_dwordx4 v[216:219], v[240:241], off
	global_load_dwordx4 v[232:235], v[240:241], off offset:64
	global_load_dwordx4 v[236:239], v[240:241], off offset:512
	s_nop 0
	global_load_dwordx4 v[240:243], v[240:241], off offset:576
	v_lshlrev_b64 v[208:209], 13, v[208:209]
	v_lshlrev_b64 v[210:211], 13, v[210:211]
	v_lshlrev_b64 v[214:215], 13, v[214:215]
	v_lshl_add_u64 v[208:209], s[78:79], 0, v[208:209]
	s_waitcnt vmcnt(15)
	v_pk_add_f32 v[144:145], v[144:145], v[64:65]
	v_pk_add_f32 v[142:143], v[142:143], v[62:63]
	s_waitcnt vmcnt(12)
	v_pk_add_f32 v[132:133], v[44:45], v[132:133]
	v_pk_add_f32 v[130:131], v[42:43], v[130:131]
	v_lshl_add_u64 v[212:213], s[78:79], 0, v[212:213]
	v_lshl_add_u64 v[210:211], s[78:79], 0, v[210:211]
	v_lshl_add_u64 v[214:215], s[78:79], 0, v[214:215]
	v_lshl_add_u64 v[208:209], v[208:209], 0, v[206:207]
	v_pk_add_f32 v[140:141], v[140:141], v[60:61]
	v_pk_add_f32 v[138:139], v[138:139], v[58:59]
	v_pk_add_f32 v[136:137], v[48:49], v[136:137]
	v_pk_add_f32 v[134:135], v[46:47], v[134:135]
	s_waitcnt vmcnt(11)
	v_pk_add_f32 v[176:177], v[176:177], v[56:57]
	v_pk_add_f32 v[174:175], v[174:175], v[54:55]
	s_waitcnt vmcnt(10)
	v_pk_add_f32 v[172:173], v[172:173], v[52:53]
	v_pk_add_f32 v[170:171], v[170:171], v[50:51]
	s_waitcnt vmcnt(9)
	v_pk_add_f32 v[164:165], v[32:33], v[164:165]
	v_pk_add_f32 v[162:163], v[30:31], v[162:163]
	s_waitcnt vmcnt(8)
	v_pk_add_f32 v[156:157], v[28:29], v[156:157]
	v_pk_add_f32 v[154:155], v[26:27], v[154:155]
	s_waitcnt vmcnt(7)
	v_pk_add_f32 v[168:169], v[168:169], v[40:41]
	v_pk_add_f32 v[166:167], v[166:167], v[38:39]
	s_waitcnt vmcnt(6)
	v_pk_add_f32 v[160:161], v[160:161], v[36:37]
	v_pk_add_f32 v[158:159], v[158:159], v[34:35]
	s_waitcnt vmcnt(5)
	v_pk_add_f32 v[152:153], v[16:17], v[152:153]
	v_pk_add_f32 v[150:151], v[14:15], v[150:151]
	s_waitcnt vmcnt(4)
	v_pk_add_f32 v[148:149], v[12:13], v[148:149]
	v_pk_add_f32 v[146:147], v[10:11], v[146:147]
	v_lshl_add_u64 v[212:213], v[212:213], 0, v[206:207]
	v_lshl_add_u64 v[210:211], v[210:211], 0, v[206:207]
	v_lshl_add_u64 v[206:207], v[214:215], 0, v[206:207]
	global_store_dwordx4 v[208:209], v[142:145], off
	global_store_dwordx4 v[208:209], v[138:141], off offset:64
	global_store_dwordx4 v[208:209], v[134:137], off offset:512
	global_store_dwordx4 v[208:209], v[130:133], off offset:576
	global_store_dwordx4 v[210:211], v[174:177], off
	global_store_dwordx4 v[210:211], v[170:173], off offset:64
	global_store_dwordx4 v[210:211], v[162:165], off offset:512
	global_store_dwordx4 v[210:211], v[154:157], off offset:576
	global_store_dwordx4 v[206:207], v[166:169], off
	global_store_dwordx4 v[206:207], v[158:161], off offset:64
	global_store_dwordx4 v[206:207], v[150:153], off offset:512
	global_store_dwordx4 v[206:207], v[146:149], off offset:576
	s_mov_b64 s[48:49], 0
	s_waitcnt vmcnt(15)
	v_pk_add_f32 v[132:133], v[24:25], v[218:219]
	v_pk_add_f32 v[130:131], v[22:23], v[216:217]
	s_waitcnt vmcnt(14)
	v_pk_add_f32 v[136:137], v[20:21], v[234:235]
	v_pk_add_f32 v[134:135], v[18:19], v[232:233]
	s_waitcnt vmcnt(13)
	v_pk_add_f32 v[140:141], v[8:9], v[238:239]
	v_pk_add_f32 v[138:139], v[6:7], v[236:237]
	s_waitcnt vmcnt(12)
	v_pk_add_f32 v[144:145], v[4:5], v[242:243]
	v_pk_add_f32 v[142:143], v[2:3], v[240:241]
	global_store_dwordx4 v[212:213], v[130:133], off
	global_store_dwordx4 v[212:213], v[134:137], off offset:64
	global_store_dwordx4 v[212:213], v[138:141], off offset:512
	global_store_dwordx4 v[212:213], v[142:145], off offset:576
